# GEMM K-loops: LDS-DMA addresses taken from scalar bases + 32-bit lane offsets (16 v_lshl_add_u64 per wave and K-step removed in P1 and P6)
# baseline (speedup 1.0000x reference)
.LBB0_109:
	ds_read_b128 v[144:147], v151
	ds_read_b128 v[154:157], v151 offset:1024
	ds_read_b128 v[158:161], v151 offset:2048
	ds_read_b128 v[162:165], v151 offset:3072
	ds_read_b128 v[166:169], v152
	ds_read_b128 v[170:173], v152 offset:1024
	ds_read_b128 v[178:181], v152 offset:2048
	ds_read_b128 v[182:185], v152 offset:3072
	s_add_u32 s64, s62, 0xfff80080
	s_addc_u32 s65, s63, -1
	s_cmp_eq_u32 s88, 28
	s_cselect_b32 s67, s31, s65
	s_cselect_b32 s66, s84, s64
	s_cselect_b32 s65, s21, s87
	s_cselect_b32 s64, s85, s86
	s_add_i32 m0, s61, 0xc000
	ds_read_b128 v[186:189], v153
	ds_read_b128 v[190:193], v153 offset:1024
	ds_read_b128 v[194:197], v153 offset:2048
	ds_read_b128 v[198:201], v153 offset:3072
	ds_read_b128 v[202:205], v153 offset:4096
	ds_read_b128 v[206:209], v153 offset:5120
	ds_read_b128 v[210:213], v153 offset:6144
	ds_read_b128 v[214:217], v153 offset:7168
	global_load_lds_dwordx4 v136, s[62:63]
	s_add_i32 m0, s61, 0xe000
	s_nop 0
	global_load_lds_dwordx4 v138, s[62:63]
	s_waitcnt vmcnt(8)
	s_waitcnt lgkmcnt(0)
	s_barrier
	s_setprio 1
	s_waitcnt lgkmcnt(0)
	v_mfma_f32_16x16x32_bf16 v[124:127], v[144:147], v[186:189], v[124:127]
	v_mfma_f32_16x16x32_bf16 v[120:123], v[158:161], v[186:189], v[120:123]
	v_mfma_f32_16x16x32_bf16 v[116:119], v[144:147], v[194:197], v[116:119]
	v_mfma_f32_16x16x32_bf16 v[108:111], v[158:161], v[194:197], v[108:111]
	v_mfma_f32_16x16x32_bf16 v[100:103], v[144:147], v[202:205], v[100:103]
	v_mfma_f32_16x16x32_bf16 v[92:95], v[158:161], v[202:205], v[92:95]
	v_mfma_f32_16x16x32_bf16 v[84:87], v[144:147], v[210:213], v[84:87]
	v_mfma_f32_16x16x32_bf16 v[76:79], v[158:161], v[210:213], v[76:79]
	v_mfma_f32_16x16x32_bf16 v[124:127], v[154:157], v[190:193], v[124:127]
	v_mfma_f32_16x16x32_bf16 v[120:123], v[162:165], v[190:193], v[120:123]
	v_mfma_f32_16x16x32_bf16 v[116:119], v[154:157], v[198:201], v[116:119]
	v_mfma_f32_16x16x32_bf16 v[108:111], v[162:165], v[198:201], v[108:111]
	v_mfma_f32_16x16x32_bf16 v[100:103], v[154:157], v[206:209], v[100:103]
	v_mfma_f32_16x16x32_bf16 v[92:95], v[162:165], v[206:209], v[92:95]
	v_mfma_f32_16x16x32_bf16 v[84:87], v[154:157], v[214:217], v[84:87]
	v_mfma_f32_16x16x32_bf16 v[76:79], v[162:165], v[214:217], v[76:79]
	s_setprio 0
	s_setprio 1
	v_mfma_f32_16x16x32_bf16 v[112:115], v[166:169], v[186:189], v[112:115]
	v_mfma_f32_16x16x32_bf16 v[104:107], v[178:181], v[186:189], v[104:107]
	v_mfma_f32_16x16x32_bf16 v[96:99], v[166:169], v[194:197], v[96:99]
	v_mfma_f32_16x16x32_bf16 v[88:91], v[178:181], v[194:197], v[88:91]
	v_mfma_f32_16x16x32_bf16 v[80:83], v[166:169], v[202:205], v[80:83]
	v_mfma_f32_16x16x32_bf16 v[72:75], v[178:181], v[202:205], v[72:75]
	v_mfma_f32_16x16x32_bf16 v[68:71], v[166:169], v[210:213], v[68:71]
	v_mfma_f32_16x16x32_bf16 v[64:67], v[178:181], v[210:213], v[64:67]
	v_mfma_f32_16x16x32_bf16 v[112:115], v[170:173], v[190:193], v[112:115]
	v_mfma_f32_16x16x32_bf16 v[104:107], v[182:185], v[190:193], v[104:107]
	v_mfma_f32_16x16x32_bf16 v[96:99], v[170:173], v[198:201], v[96:99]
	v_mfma_f32_16x16x32_bf16 v[88:91], v[182:185], v[198:201], v[88:91]
	v_mfma_f32_16x16x32_bf16 v[80:83], v[170:173], v[206:209], v[80:83]
	v_mfma_f32_16x16x32_bf16 v[72:75], v[182:185], v[206:209], v[72:75]
	v_mfma_f32_16x16x32_bf16 v[68:71], v[170:173], v[214:217], v[68:71]
	v_mfma_f32_16x16x32_bf16 v[64:67], v[182:185], v[214:217], v[64:67]
	s_setprio 0
	s_barrier
	s_add_i32 s89, s80, s69
	s_mov_b32 m0, s89
	ds_read_b128 v[186:189], v153 offset:16384
	ds_read_b128 v[190:193], v153 offset:17408
	ds_read_b128 v[194:197], v153 offset:18432
	ds_read_b128 v[198:201], v153 offset:19456
	ds_read_b128 v[202:205], v153 offset:20480
	ds_read_b128 v[206:209], v153 offset:21504
	ds_read_b128 v[210:213], v153 offset:22528
	ds_read_b128 v[214:217], v153 offset:23552
	global_load_lds_dwordx4 v132, s[64:65]
	s_add_i32 m0, s89, 0x2000
	s_add_u32 s90, s64, 0x80000
	s_addc_u32 s91, s65, 0
	s_add_i32 s89, s81, s69
	global_load_lds_dwordx4 v128, s[64:65]
	s_mov_b32 m0, s89
	s_add_u32 s92, s66, 0x80
	s_addc_u32 s93, s67, 0
	global_load_lds_dwordx4 v132, s[90:91]
	s_add_i32 m0, s89, 0x2000
	s_nop 0
	global_load_lds_dwordx4 v128, s[90:91]
	s_mov_b32 m0, s61
	s_nop 0
	global_load_lds_dwordx4 v134, s[66:67]
	s_mov_b32 m0, s72
	s_nop 0
	global_load_lds_dwordx4 v130, s[66:67]
	s_waitcnt vmcnt(8)
	s_waitcnt lgkmcnt(0)
	s_barrier
	s_setprio 1
	s_waitcnt lgkmcnt(0)
	v_mfma_f32_16x16x32_bf16 v[60:63], v[144:147], v[186:189], v[60:63]
	v_mfma_f32_16x16x32_bf16 v[56:59], v[158:161], v[186:189], v[56:59]
	v_mfma_f32_16x16x32_bf16 v[52:55], v[144:147], v[194:197], v[52:55]
	v_mfma_f32_16x16x32_bf16 v[44:47], v[158:161], v[194:197], v[44:47]
	v_mfma_f32_16x16x32_bf16 v[36:39], v[144:147], v[202:205], v[36:39]
	v_mfma_f32_16x16x32_bf16 v[28:31], v[158:161], v[202:205], v[28:31]
	v_mfma_f32_16x16x32_bf16 v[20:23], v[144:147], v[210:213], v[20:23]
	v_mfma_f32_16x16x32_bf16 v[12:15], v[158:161], v[210:213], v[12:15]
	v_mfma_f32_16x16x32_bf16 v[60:63], v[154:157], v[190:193], v[60:63]
	v_mfma_f32_16x16x32_bf16 v[56:59], v[162:165], v[190:193], v[56:59]
	v_mfma_f32_16x16x32_bf16 v[52:55], v[154:157], v[198:201], v[52:55]
	v_mfma_f32_16x16x32_bf16 v[44:47], v[162:165], v[198:201], v[44:47]
	v_mfma_f32_16x16x32_bf16 v[36:39], v[154:157], v[206:209], v[36:39]
	v_mfma_f32_16x16x32_bf16 v[28:31], v[162:165], v[206:209], v[28:31]
	v_mfma_f32_16x16x32_bf16 v[20:23], v[154:157], v[214:217], v[20:23]
	v_mfma_f32_16x16x32_bf16 v[12:15], v[162:165], v[214:217], v[12:15]
	s_setprio 0
	s_setprio 1
	v_mfma_f32_16x16x32_bf16 v[48:51], v[166:169], v[186:189], v[48:51]
	v_mfma_f32_16x16x32_bf16 v[40:43], v[178:181], v[186:189], v[40:43]
	v_mfma_f32_16x16x32_bf16 v[32:35], v[166:169], v[194:197], v[32:35]
	v_mfma_f32_16x16x32_bf16 v[24:27], v[178:181], v[194:197], v[24:27]
	v_mfma_f32_16x16x32_bf16 v[16:19], v[166:169], v[202:205], v[16:19]
	v_mfma_f32_16x16x32_bf16 v[8:11], v[178:181], v[202:205], v[8:11]
	v_mfma_f32_16x16x32_bf16 v[4:7], v[166:169], v[210:213], v[4:7]
	v_mfma_f32_16x16x32_bf16 v[0:3], v[178:181], v[210:213], v[0:3]
	v_mfma_f32_16x16x32_bf16 v[48:51], v[170:173], v[190:193], v[48:51]
	v_mfma_f32_16x16x32_bf16 v[40:43], v[182:185], v[190:193], v[40:43]
	v_mfma_f32_16x16x32_bf16 v[32:35], v[170:173], v[198:201], v[32:35]
	v_mfma_f32_16x16x32_bf16 v[24:27], v[182:185], v[198:201], v[24:27]
	v_mfma_f32_16x16x32_bf16 v[16:19], v[170:173], v[206:209], v[16:19]
	v_mfma_f32_16x16x32_bf16 v[8:11], v[182:185], v[206:209], v[8:11]
	v_mfma_f32_16x16x32_bf16 v[4:7], v[170:173], v[214:217], v[4:7]
	v_mfma_f32_16x16x32_bf16 v[0:3], v[182:185], v[214:217], v[0:3]
	s_setprio 0
	s_barrier
	s_add_i32 s89, 16, 0x18000
	s_add_i32 s90, 16, 0x1c000
	v_add_u32_e32 v162, s89, v149
	v_add_u32_e32 v182, s90, v149
	ds_read_b128 v[144:147], v162
	ds_read_b128 v[154:157], v162 offset:1024
	ds_read_b128 v[158:161], v162 offset:2048
	ds_read_b128 v[162:165], v162 offset:3072
	ds_read_b128 v[166:169], v182
	ds_read_b128 v[170:173], v182 offset:1024
	ds_read_b128 v[178:181], v182 offset:2048
	ds_read_b128 v[182:185], v182 offset:3072
	s_add_u32 s66, s66, 0x80000
	s_addc_u32 s67, s67, 0
	s_mov_b32 m0, s73
	ds_read_b128 v[186:189], v153 offset:32768
	ds_read_b128 v[190:193], v153 offset:33792
	ds_read_b128 v[194:197], v153 offset:34816
	ds_read_b128 v[198:201], v153 offset:35840
	ds_read_b128 v[202:205], v153 offset:36864
	ds_read_b128 v[206:209], v153 offset:37888
	ds_read_b128 v[210:213], v153 offset:38912
	ds_read_b128 v[214:217], v153 offset:39936
	global_load_lds_dwordx4 v134, s[66:67]
	s_mov_b32 m0, s74
	s_nop 0
	global_load_lds_dwordx4 v130, s[66:67]
	s_waitcnt vmcnt(8)
	s_waitcnt lgkmcnt(0)
	s_barrier
	s_setprio 1
	s_waitcnt lgkmcnt(0)
	v_mfma_f32_16x16x32_bf16 v[124:127], v[144:147], v[186:189], v[124:127]
	v_mfma_f32_16x16x32_bf16 v[120:123], v[158:161], v[186:189], v[120:123]
	v_mfma_f32_16x16x32_bf16 v[116:119], v[144:147], v[194:197], v[116:119]
	v_mfma_f32_16x16x32_bf16 v[108:111], v[158:161], v[194:197], v[108:111]
	v_mfma_f32_16x16x32_bf16 v[100:103], v[144:147], v[202:205], v[100:103]
	v_mfma_f32_16x16x32_bf16 v[92:95], v[158:161], v[202:205], v[92:95]
	v_mfma_f32_16x16x32_bf16 v[84:87], v[144:147], v[210:213], v[84:87]
	v_mfma_f32_16x16x32_bf16 v[76:79], v[158:161], v[210:213], v[76:79]
	v_mfma_f32_16x16x32_bf16 v[124:127], v[154:157], v[190:193], v[124:127]
	v_mfma_f32_16x16x32_bf16 v[120:123], v[162:165], v[190:193], v[120:123]
	v_mfma_f32_16x16x32_bf16 v[116:119], v[154:157], v[198:201], v[116:119]
	v_mfma_f32_16x16x32_bf16 v[108:111], v[162:165], v[198:201], v[108:111]
	v_mfma_f32_16x16x32_bf16 v[100:103], v[154:157], v[206:209], v[100:103]
	v_mfma_f32_16x16x32_bf16 v[92:95], v[162:165], v[206:209], v[92:95]
	v_mfma_f32_16x16x32_bf16 v[84:87], v[154:157], v[214:217], v[84:87]
	v_mfma_f32_16x16x32_bf16 v[76:79], v[162:165], v[214:217], v[76:79]
	s_setprio 0
	s_setprio 1
	v_mfma_f32_16x16x32_bf16 v[112:115], v[166:169], v[186:189], v[112:115]
	v_mfma_f32_16x16x32_bf16 v[104:107], v[178:181], v[186:189], v[104:107]
	v_mfma_f32_16x16x32_bf16 v[96:99], v[166:169], v[194:197], v[96:99]
	v_mfma_f32_16x16x32_bf16 v[88:91], v[178:181], v[194:197], v[88:91]
	v_mfma_f32_16x16x32_bf16 v[80:83], v[166:169], v[202:205], v[80:83]
	v_mfma_f32_16x16x32_bf16 v[72:75], v[178:181], v[202:205], v[72:75]
	v_mfma_f32_16x16x32_bf16 v[68:71], v[166:169], v[210:213], v[68:71]
	v_mfma_f32_16x16x32_bf16 v[64:67], v[178:181], v[210:213], v[64:67]
	v_mfma_f32_16x16x32_bf16 v[112:115], v[170:173], v[190:193], v[112:115]
	v_mfma_f32_16x16x32_bf16 v[104:107], v[182:185], v[190:193], v[104:107]
	v_mfma_f32_16x16x32_bf16 v[96:99], v[170:173], v[198:201], v[96:99]
	v_mfma_f32_16x16x32_bf16 v[88:91], v[182:185], v[198:201], v[88:91]
	v_mfma_f32_16x16x32_bf16 v[80:83], v[170:173], v[206:209], v[80:83]
	v_mfma_f32_16x16x32_bf16 v[72:75], v[182:185], v[206:209], v[72:75]
	v_mfma_f32_16x16x32_bf16 v[68:71], v[170:173], v[214:217], v[68:71]
	v_mfma_f32_16x16x32_bf16 v[64:67], v[182:185], v[214:217], v[64:67]
	s_setprio 0
	s_barrier
	s_add_i32 s66, s89, s69
	s_mov_b32 m0, s66
	ds_read_b128 v[186:189], v153 offset:49152
	ds_read_b128 v[190:193], v153 offset:50176
	ds_read_b128 v[194:197], v153 offset:51200
	ds_read_b128 v[198:201], v153 offset:52224
	ds_read_b128 v[202:205], v153 offset:53248
	ds_read_b128 v[206:209], v153 offset:54272
	ds_read_b128 v[210:213], v153 offset:55296
	ds_read_b128 v[214:217], v153 offset:56320
	s_add_u32 s100, s64, 0x80
	s_addc_u32 s101, s65, 0
	s_nop 0
	global_load_lds_dwordx4 v132, s[100:101]
	s_add_i32 m0, s66, 0x2000
	s_add_u32 s64, s64, 0x80080
	s_addc_u32 s65, s65, 0
	s_add_i32 s66, s90, s69
	s_add_u32 s100, s64, 0xfff80000
	s_addc_u32 s101, s65, -1
	s_nop 0
	global_load_lds_dwordx4 v128, s[100:101]
	s_mov_b32 m0, s66
	s_nop 0
	global_load_lds_dwordx4 v132, s[64:65]
	s_add_i32 m0, s66, 0x2000
	s_nop 0
	global_load_lds_dwordx4 v128, s[64:65]
	s_mov_b32 m0, s76
	s_nop 0
	global_load_lds_dwordx4 v134, s[92:93]
	s_mov_b32 m0, s77
	s_nop 0
	global_load_lds_dwordx4 v130, s[92:93]
	s_waitcnt vmcnt(8)
	s_waitcnt lgkmcnt(0)
	s_barrier
	s_setprio 1
	s_waitcnt lgkmcnt(0)
	v_mfma_f32_16x16x32_bf16 v[60:63], v[144:147], v[186:189], v[60:63]
	v_mfma_f32_16x16x32_bf16 v[56:59], v[158:161], v[186:189], v[56:59]
	v_mfma_f32_16x16x32_bf16 v[52:55], v[144:147], v[194:197], v[52:55]
	v_mfma_f32_16x16x32_bf16 v[44:47], v[158:161], v[194:197], v[44:47]
	v_mfma_f32_16x16x32_bf16 v[36:39], v[144:147], v[202:205], v[36:39]
	v_mfma_f32_16x16x32_bf16 v[28:31], v[158:161], v[202:205], v[28:31]
	v_mfma_f32_16x16x32_bf16 v[20:23], v[144:147], v[210:213], v[20:23]
	v_mfma_f32_16x16x32_bf16 v[12:15], v[158:161], v[210:213], v[12:15]
	v_mfma_f32_16x16x32_bf16 v[60:63], v[154:157], v[190:193], v[60:63]
	v_mfma_f32_16x16x32_bf16 v[56:59], v[162:165], v[190:193], v[56:59]
	v_mfma_f32_16x16x32_bf16 v[52:55], v[154:157], v[198:201], v[52:55]
	v_mfma_f32_16x16x32_bf16 v[44:47], v[162:165], v[198:201], v[44:47]
	v_mfma_f32_16x16x32_bf16 v[36:39], v[154:157], v[206:209], v[36:39]
	v_mfma_f32_16x16x32_bf16 v[28:31], v[162:165], v[206:209], v[28:31]
	v_mfma_f32_16x16x32_bf16 v[20:23], v[154:157], v[214:217], v[20:23]
	v_mfma_f32_16x16x32_bf16 v[12:15], v[162:165], v[214:217], v[12:15]
	s_setprio 0
	s_setprio 1
	v_mfma_f32_16x16x32_bf16 v[48:51], v[166:169], v[186:189], v[48:51]
	v_mfma_f32_16x16x32_bf16 v[40:43], v[178:181], v[186:189], v[40:43]
	v_mfma_f32_16x16x32_bf16 v[32:35], v[166:169], v[194:197], v[32:35]
	v_mfma_f32_16x16x32_bf16 v[24:27], v[178:181], v[194:197], v[24:27]
	v_mfma_f32_16x16x32_bf16 v[16:19], v[166:169], v[202:205], v[16:19]
	v_mfma_f32_16x16x32_bf16 v[8:11], v[178:181], v[202:205], v[8:11]
	v_mfma_f32_16x16x32_bf16 v[4:7], v[166:169], v[210:213], v[4:7]
	v_mfma_f32_16x16x32_bf16 v[0:3], v[178:181], v[210:213], v[0:3]
	v_mfma_f32_16x16x32_bf16 v[48:51], v[170:173], v[190:193], v[48:51]
	v_mfma_f32_16x16x32_bf16 v[40:43], v[182:185], v[190:193], v[40:43]
	v_mfma_f32_16x16x32_bf16 v[32:35], v[170:173], v[198:201], v[32:35]
	v_mfma_f32_16x16x32_bf16 v[24:27], v[182:185], v[198:201], v[24:27]
	v_mfma_f32_16x16x32_bf16 v[16:19], v[170:173], v[206:209], v[16:19]
	v_mfma_f32_16x16x32_bf16 v[8:11], v[182:185], v[206:209], v[8:11]
	v_mfma_f32_16x16x32_bf16 v[4:7], v[170:173], v[214:217], v[4:7]
	v_mfma_f32_16x16x32_bf16 v[0:3], v[182:185], v[214:217], v[0:3]
	s_setprio 0
	s_barrier
	s_add_i32 s88, s88, 2
	s_add_u32 s62, s62, 0x100
	s_addc_u32 s63, s63, 0
	s_add_u32 s86, s86, 0x100
	s_addc_u32 s87, s87, 0
	s_cmp_gt_u32 s88, 29
	s_cbranch_scc0 .LBB0_109
	s_and_b64 vcc, exec, s[14:15]
	s_cbranch_vccz .LBB0_112
	s_barrier

.LBB0_563:
	ds_read_b128 v[148:151], v145
	ds_read_b128 v[152:155], v145 offset:1024
	ds_read_b128 v[156:159], v145 offset:2048
	ds_read_b128 v[160:163], v145 offset:3072
	ds_read_b128 v[164:167], v146
	ds_read_b128 v[168:171], v146 offset:1024
	ds_read_b128 v[172:175], v146 offset:2048
	ds_read_b128 v[176:179], v146 offset:3072
	s_add_u32 s36, s30, 0xfff80080
	s_addc_u32 s37, s31, -1
	s_cmp_eq_u32 s59, 28
	s_cselect_b32 s39, s23, s37
	s_cselect_b32 s38, s55, s36
	s_cselect_b32 s37, s21, s58
	s_cselect_b32 s36, s56, s57
	s_add_i32 m0, s29, 0xc000
	ds_read_b128 v[180:183], v147
	ds_read_b128 v[184:187], v147 offset:1024
	ds_read_b128 v[188:191], v147 offset:2048
	ds_read_b128 v[192:195], v147 offset:3072
	ds_read_b128 v[196:199], v147 offset:4096
	ds_read_b128 v[200:203], v147 offset:5120
	ds_read_b128 v[204:207], v147 offset:6144
	ds_read_b128 v[208:211], v147 offset:7168
	global_load_lds_dwordx4 v132, s[30:31]
	s_add_i32 m0, s29, 0xe000
	s_nop 0
	global_load_lds_dwordx4 v134, s[30:31]
	s_waitcnt vmcnt(8)
	s_waitcnt lgkmcnt(0)
	s_barrier
	s_setprio 1
	s_waitcnt lgkmcnt(0)
	v_mfma_f32_16x16x32_bf16 v[124:127], v[148:151], v[180:183], v[124:127]
	v_mfma_f32_16x16x32_bf16 v[120:123], v[156:159], v[180:183], v[120:123]
	v_mfma_f32_16x16x32_bf16 v[112:115], v[148:151], v[188:191], v[112:115]
	v_mfma_f32_16x16x32_bf16 v[108:111], v[156:159], v[188:191], v[108:111]
	v_mfma_f32_16x16x32_bf16 v[96:99], v[148:151], v[196:199], v[96:99]
	v_mfma_f32_16x16x32_bf16 v[92:95], v[156:159], v[196:199], v[92:95]
	v_mfma_f32_16x16x32_bf16 v[80:83], v[148:151], v[204:207], v[80:83]
	v_mfma_f32_16x16x32_bf16 v[76:79], v[156:159], v[204:207], v[76:79]
	v_mfma_f32_16x16x32_bf16 v[124:127], v[152:155], v[184:187], v[124:127]
	v_mfma_f32_16x16x32_bf16 v[120:123], v[160:163], v[184:187], v[120:123]
	v_mfma_f32_16x16x32_bf16 v[112:115], v[152:155], v[192:195], v[112:115]
	v_mfma_f32_16x16x32_bf16 v[108:111], v[160:163], v[192:195], v[108:111]
	v_mfma_f32_16x16x32_bf16 v[96:99], v[152:155], v[200:203], v[96:99]
	v_mfma_f32_16x16x32_bf16 v[92:95], v[160:163], v[200:203], v[92:95]
	v_mfma_f32_16x16x32_bf16 v[80:83], v[152:155], v[208:211], v[80:83]
	v_mfma_f32_16x16x32_bf16 v[76:79], v[160:163], v[208:211], v[76:79]
	s_setprio 0
	s_setprio 1
	v_mfma_f32_16x16x32_bf16 v[116:119], v[164:167], v[180:183], v[116:119]
	v_mfma_f32_16x16x32_bf16 v[104:107], v[172:175], v[180:183], v[104:107]
	v_mfma_f32_16x16x32_bf16 v[100:103], v[164:167], v[188:191], v[100:103]
	v_mfma_f32_16x16x32_bf16 v[88:91], v[172:175], v[188:191], v[88:91]
	v_mfma_f32_16x16x32_bf16 v[84:87], v[164:167], v[196:199], v[84:87]
	v_mfma_f32_16x16x32_bf16 v[72:75], v[172:175], v[196:199], v[72:75]
	v_mfma_f32_16x16x32_bf16 v[68:71], v[164:167], v[204:207], v[68:71]
	v_mfma_f32_16x16x32_bf16 v[64:67], v[172:175], v[204:207], v[64:67]
	v_mfma_f32_16x16x32_bf16 v[116:119], v[168:171], v[184:187], v[116:119]
	v_mfma_f32_16x16x32_bf16 v[104:107], v[176:179], v[184:187], v[104:107]
	v_mfma_f32_16x16x32_bf16 v[100:103], v[168:171], v[192:195], v[100:103]
	v_mfma_f32_16x16x32_bf16 v[88:91], v[176:179], v[192:195], v[88:91]
	v_mfma_f32_16x16x32_bf16 v[84:87], v[168:171], v[200:203], v[84:87]
	v_mfma_f32_16x16x32_bf16 v[72:75], v[176:179], v[200:203], v[72:75]
	v_mfma_f32_16x16x32_bf16 v[68:71], v[168:171], v[208:211], v[68:71]
	v_mfma_f32_16x16x32_bf16 v[64:67], v[176:179], v[208:211], v[64:67]
	s_setprio 0
	s_barrier
	s_add_i32 s60, s52, s42
	s_mov_b32 m0, s60
	ds_read_b128 v[180:183], v147 offset:16384
	ds_read_b128 v[184:187], v147 offset:17408
	ds_read_b128 v[188:191], v147 offset:18432
	ds_read_b128 v[192:195], v147 offset:19456
	ds_read_b128 v[196:199], v147 offset:20480
	ds_read_b128 v[200:203], v147 offset:21504
	ds_read_b128 v[204:207], v147 offset:22528
	ds_read_b128 v[208:211], v147 offset:23552
	global_load_lds_dwordx4 v128, s[36:37]
	s_add_i32 m0, s60, 0x2000
	s_add_u32 s60, s36, 0x80000
	s_addc_u32 s61, s37, 0
	s_add_i32 s62, s53, s42
	global_load_lds_dwordx4 v130, s[36:37]
	s_mov_b32 m0, s62
	s_add_u32 s64, s38, 0x80
	s_addc_u32 s65, s39, 0
	global_load_lds_dwordx4 v128, s[60:61]
	s_add_i32 m0, s62, 0x2000
	s_nop 0
	global_load_lds_dwordx4 v130, s[60:61]
	s_mov_b32 m0, s29
	s_nop 0
	global_load_lds_dwordx4 v128, s[38:39]
	s_mov_b32 m0, s43
	s_nop 0
	global_load_lds_dwordx4 v130, s[38:39]
	s_waitcnt vmcnt(8)
	s_waitcnt lgkmcnt(0)
	s_barrier
	s_setprio 1
	s_waitcnt lgkmcnt(0)
	v_mfma_f32_16x16x32_bf16 v[60:63], v[148:151], v[180:183], v[60:63]
	v_mfma_f32_16x16x32_bf16 v[56:59], v[156:159], v[180:183], v[56:59]
	v_mfma_f32_16x16x32_bf16 v[48:51], v[148:151], v[188:191], v[48:51]
	v_mfma_f32_16x16x32_bf16 v[44:47], v[156:159], v[188:191], v[44:47]
	v_mfma_f32_16x16x32_bf16 v[32:35], v[148:151], v[196:199], v[32:35]
	v_mfma_f32_16x16x32_bf16 v[28:31], v[156:159], v[196:199], v[28:31]
	v_mfma_f32_16x16x32_bf16 v[16:19], v[148:151], v[204:207], v[16:19]
	v_mfma_f32_16x16x32_bf16 v[12:15], v[156:159], v[204:207], v[12:15]
	v_mfma_f32_16x16x32_bf16 v[60:63], v[152:155], v[184:187], v[60:63]
	v_mfma_f32_16x16x32_bf16 v[56:59], v[160:163], v[184:187], v[56:59]
	v_mfma_f32_16x16x32_bf16 v[48:51], v[152:155], v[192:195], v[48:51]
	v_mfma_f32_16x16x32_bf16 v[44:47], v[160:163], v[192:195], v[44:47]
	v_mfma_f32_16x16x32_bf16 v[32:35], v[152:155], v[200:203], v[32:35]
	v_mfma_f32_16x16x32_bf16 v[28:31], v[160:163], v[200:203], v[28:31]
	v_mfma_f32_16x16x32_bf16 v[16:19], v[152:155], v[208:211], v[16:19]
	v_mfma_f32_16x16x32_bf16 v[12:15], v[160:163], v[208:211], v[12:15]
	s_setprio 0
	s_setprio 1
	v_mfma_f32_16x16x32_bf16 v[52:55], v[164:167], v[180:183], v[52:55]
	v_mfma_f32_16x16x32_bf16 v[40:43], v[172:175], v[180:183], v[40:43]
	v_mfma_f32_16x16x32_bf16 v[36:39], v[164:167], v[188:191], v[36:39]
	v_mfma_f32_16x16x32_bf16 v[24:27], v[172:175], v[188:191], v[24:27]
	v_mfma_f32_16x16x32_bf16 v[20:23], v[164:167], v[196:199], v[20:23]
	v_mfma_f32_16x16x32_bf16 v[8:11], v[172:175], v[196:199], v[8:11]
	v_mfma_f32_16x16x32_bf16 v[4:7], v[164:167], v[204:207], v[4:7]
	v_mfma_f32_16x16x32_bf16 v[0:3], v[172:175], v[204:207], v[0:3]
	v_mfma_f32_16x16x32_bf16 v[52:55], v[168:171], v[184:187], v[52:55]
	v_mfma_f32_16x16x32_bf16 v[40:43], v[176:179], v[184:187], v[40:43]
	v_mfma_f32_16x16x32_bf16 v[36:39], v[168:171], v[192:195], v[36:39]
	v_mfma_f32_16x16x32_bf16 v[24:27], v[176:179], v[192:195], v[24:27]
	v_mfma_f32_16x16x32_bf16 v[20:23], v[168:171], v[200:203], v[20:23]
	v_mfma_f32_16x16x32_bf16 v[8:11], v[176:179], v[200:203], v[8:11]
	v_mfma_f32_16x16x32_bf16 v[4:7], v[168:171], v[208:211], v[4:7]
	v_mfma_f32_16x16x32_bf16 v[0:3], v[176:179], v[208:211], v[0:3]
	s_setprio 0
	s_barrier
	s_add_i32 s60, 16, 0x18000
	s_add_i32 s61, 16, 0x1c000
	v_add_u32_e32 v160, s60, v143
	v_add_u32_e32 v176, s61, v143
	ds_read_b128 v[148:151], v160
	ds_read_b128 v[152:155], v160 offset:1024
	ds_read_b128 v[156:159], v160 offset:2048
	ds_read_b128 v[160:163], v160 offset:3072
	ds_read_b128 v[164:167], v176
	ds_read_b128 v[168:171], v176 offset:1024
	ds_read_b128 v[172:175], v176 offset:2048
	ds_read_b128 v[176:179], v176 offset:3072
	s_add_u32 s38, s38, 0x80000
	s_addc_u32 s39, s39, 0
	s_mov_b32 m0, s44
	ds_read_b128 v[180:183], v147 offset:32768
	ds_read_b128 v[184:187], v147 offset:33792
	ds_read_b128 v[188:191], v147 offset:34816
	ds_read_b128 v[192:195], v147 offset:35840
	ds_read_b128 v[196:199], v147 offset:36864
	ds_read_b128 v[200:203], v147 offset:37888
	ds_read_b128 v[204:207], v147 offset:38912
	ds_read_b128 v[208:211], v147 offset:39936
	global_load_lds_dwordx4 v128, s[38:39]
	s_mov_b32 m0, s45
	s_nop 0
	global_load_lds_dwordx4 v130, s[38:39]
	s_waitcnt vmcnt(8)
	s_waitcnt lgkmcnt(0)
	s_barrier
	s_setprio 1
	s_waitcnt lgkmcnt(0)
	v_mfma_f32_16x16x32_bf16 v[124:127], v[148:151], v[180:183], v[124:127]
	v_mfma_f32_16x16x32_bf16 v[120:123], v[156:159], v[180:183], v[120:123]
	v_mfma_f32_16x16x32_bf16 v[112:115], v[148:151], v[188:191], v[112:115]
	v_mfma_f32_16x16x32_bf16 v[108:111], v[156:159], v[188:191], v[108:111]
	v_mfma_f32_16x16x32_bf16 v[96:99], v[148:151], v[196:199], v[96:99]
	v_mfma_f32_16x16x32_bf16 v[92:95], v[156:159], v[196:199], v[92:95]
	v_mfma_f32_16x16x32_bf16 v[80:83], v[148:151], v[204:207], v[80:83]
	v_mfma_f32_16x16x32_bf16 v[76:79], v[156:159], v[204:207], v[76:79]
	v_mfma_f32_16x16x32_bf16 v[124:127], v[152:155], v[184:187], v[124:127]
	v_mfma_f32_16x16x32_bf16 v[120:123], v[160:163], v[184:187], v[120:123]
	v_mfma_f32_16x16x32_bf16 v[112:115], v[152:155], v[192:195], v[112:115]
	v_mfma_f32_16x16x32_bf16 v[108:111], v[160:163], v[192:195], v[108:111]
	v_mfma_f32_16x16x32_bf16 v[96:99], v[152:155], v[200:203], v[96:99]
	v_mfma_f32_16x16x32_bf16 v[92:95], v[160:163], v[200:203], v[92:95]
	v_mfma_f32_16x16x32_bf16 v[80:83], v[152:155], v[208:211], v[80:83]
	v_mfma_f32_16x16x32_bf16 v[76:79], v[160:163], v[208:211], v[76:79]
	s_setprio 0
	s_setprio 1
	v_mfma_f32_16x16x32_bf16 v[116:119], v[164:167], v[180:183], v[116:119]
	v_mfma_f32_16x16x32_bf16 v[104:107], v[172:175], v[180:183], v[104:107]
	v_mfma_f32_16x16x32_bf16 v[100:103], v[164:167], v[188:191], v[100:103]
	v_mfma_f32_16x16x32_bf16 v[88:91], v[172:175], v[188:191], v[88:91]
	v_mfma_f32_16x16x32_bf16 v[84:87], v[164:167], v[196:199], v[84:87]
	v_mfma_f32_16x16x32_bf16 v[72:75], v[172:175], v[196:199], v[72:75]
	v_mfma_f32_16x16x32_bf16 v[68:71], v[164:167], v[204:207], v[68:71]
	v_mfma_f32_16x16x32_bf16 v[64:67], v[172:175], v[204:207], v[64:67]
	v_mfma_f32_16x16x32_bf16 v[116:119], v[168:171], v[184:187], v[116:119]
	v_mfma_f32_16x16x32_bf16 v[104:107], v[176:179], v[184:187], v[104:107]
	v_mfma_f32_16x16x32_bf16 v[100:103], v[168:171], v[192:195], v[100:103]
	v_mfma_f32_16x16x32_bf16 v[88:91], v[176:179], v[192:195], v[88:91]
	v_mfma_f32_16x16x32_bf16 v[84:87], v[168:171], v[200:203], v[84:87]
	v_mfma_f32_16x16x32_bf16 v[72:75], v[176:179], v[200:203], v[72:75]
	v_mfma_f32_16x16x32_bf16 v[68:71], v[168:171], v[208:211], v[68:71]
	v_mfma_f32_16x16x32_bf16 v[64:67], v[176:179], v[208:211], v[64:67]
	s_setprio 0
	s_barrier
	s_add_i32 s38, s60, s42
	s_mov_b32 m0, s38
	ds_read_b128 v[180:183], v147 offset:49152
	ds_read_b128 v[184:187], v147 offset:50176
	ds_read_b128 v[188:191], v147 offset:51200
	ds_read_b128 v[192:195], v147 offset:52224
	ds_read_b128 v[196:199], v147 offset:53248
	ds_read_b128 v[200:203], v147 offset:54272
	ds_read_b128 v[204:207], v147 offset:55296
	ds_read_b128 v[208:211], v147 offset:56320
	s_add_u32 s100, s36, 0x80
	s_addc_u32 s101, s37, 0
	s_nop 0
	global_load_lds_dwordx4 v128, s[100:101]
	s_add_i32 m0, s38, 0x2000
	s_add_u32 s36, s36, 0x80080
	s_addc_u32 s37, s37, 0
	s_add_i32 s38, s61, s42
	s_add_u32 s100, s36, 0xfff80000
	s_addc_u32 s101, s37, -1
	s_nop 0
	global_load_lds_dwordx4 v130, s[100:101]
	s_mov_b32 m0, s38
	s_nop 0
	global_load_lds_dwordx4 v128, s[36:37]
	s_add_i32 m0, s38, 0x2000
	s_nop 0
	global_load_lds_dwordx4 v130, s[36:37]
	s_mov_b32 m0, s46
	s_nop 0
	global_load_lds_dwordx4 v128, s[64:65]
	s_mov_b32 m0, s47
	s_nop 0
	global_load_lds_dwordx4 v130, s[64:65]
	s_waitcnt vmcnt(8)
	s_waitcnt lgkmcnt(0)
	s_barrier
	s_setprio 1
	s_waitcnt lgkmcnt(0)
	v_mfma_f32_16x16x32_bf16 v[60:63], v[148:151], v[180:183], v[60:63]
	v_mfma_f32_16x16x32_bf16 v[56:59], v[156:159], v[180:183], v[56:59]
	v_mfma_f32_16x16x32_bf16 v[48:51], v[148:151], v[188:191], v[48:51]
	v_mfma_f32_16x16x32_bf16 v[44:47], v[156:159], v[188:191], v[44:47]
	v_mfma_f32_16x16x32_bf16 v[32:35], v[148:151], v[196:199], v[32:35]
	v_mfma_f32_16x16x32_bf16 v[28:31], v[156:159], v[196:199], v[28:31]
	v_mfma_f32_16x16x32_bf16 v[16:19], v[148:151], v[204:207], v[16:19]
	v_mfma_f32_16x16x32_bf16 v[12:15], v[156:159], v[204:207], v[12:15]
	v_mfma_f32_16x16x32_bf16 v[60:63], v[152:155], v[184:187], v[60:63]
	v_mfma_f32_16x16x32_bf16 v[56:59], v[160:163], v[184:187], v[56:59]
	v_mfma_f32_16x16x32_bf16 v[48:51], v[152:155], v[192:195], v[48:51]
	v_mfma_f32_16x16x32_bf16 v[44:47], v[160:163], v[192:195], v[44:47]
	v_mfma_f32_16x16x32_bf16 v[32:35], v[152:155], v[200:203], v[32:35]
	v_mfma_f32_16x16x32_bf16 v[28:31], v[160:163], v[200:203], v[28:31]
	v_mfma_f32_16x16x32_bf16 v[16:19], v[152:155], v[208:211], v[16:19]
	v_mfma_f32_16x16x32_bf16 v[12:15], v[160:163], v[208:211], v[12:15]
	s_setprio 0
	s_setprio 1
	v_mfma_f32_16x16x32_bf16 v[52:55], v[164:167], v[180:183], v[52:55]
	v_mfma_f32_16x16x32_bf16 v[40:43], v[172:175], v[180:183], v[40:43]
	v_mfma_f32_16x16x32_bf16 v[36:39], v[164:167], v[188:191], v[36:39]
	v_mfma_f32_16x16x32_bf16 v[24:27], v[172:175], v[188:191], v[24:27]
	v_mfma_f32_16x16x32_bf16 v[20:23], v[164:167], v[196:199], v[20:23]
	v_mfma_f32_16x16x32_bf16 v[8:11], v[172:175], v[196:199], v[8:11]
	v_mfma_f32_16x16x32_bf16 v[4:7], v[164:167], v[204:207], v[4:7]
	v_mfma_f32_16x16x32_bf16 v[0:3], v[172:175], v[204:207], v[0:3]
	v_mfma_f32_16x16x32_bf16 v[52:55], v[168:171], v[184:187], v[52:55]
	v_mfma_f32_16x16x32_bf16 v[40:43], v[176:179], v[184:187], v[40:43]
	v_mfma_f32_16x16x32_bf16 v[36:39], v[168:171], v[192:195], v[36:39]
	v_mfma_f32_16x16x32_bf16 v[24:27], v[176:179], v[192:195], v[24:27]
	v_mfma_f32_16x16x32_bf16 v[20:23], v[168:171], v[200:203], v[20:23]
	v_mfma_f32_16x16x32_bf16 v[8:11], v[176:179], v[200:203], v[8:11]
	v_mfma_f32_16x16x32_bf16 v[4:7], v[168:171], v[208:211], v[4:7]
	v_mfma_f32_16x16x32_bf16 v[0:3], v[176:179], v[208:211], v[0:3]
	s_setprio 0
	s_barrier
	s_add_i32 s59, s59, 2
	s_add_u32 s30, s30, 0x100
	s_addc_u32 s31, s31, 0
	s_add_u32 s57, s57, 0x100
	s_addc_u32 s58, s58, 0
	s_cmp_gt_u32 s59, 29
	s_cbranch_scc0 .LBB0_563
	s_and_b64 vcc, exec, s[8:9]
	s_cbranch_vccz .LBB0_566
	s_barrier

	.amdhsa_kernel _Z10hybrid_fwd4Args
		.amdhsa_group_segment_fixed_size 16
		.amdhsa_private_segment_fixed_size 0
		.amdhsa_kernarg_size 400
		.amdhsa_user_sgpr_count 2
		.amdhsa_user_sgpr_dispatch_ptr 0
		.amdhsa_user_sgpr_queue_ptr 0
		.amdhsa_user_sgpr_kernarg_segment_ptr 1
		.amdhsa_user_sgpr_dispatch_id 0
		.amdhsa_user_sgpr_kernarg_preload_length 0
		.amdhsa_user_sgpr_kernarg_preload_offset 0
		.amdhsa_user_sgpr_private_segment_size 0
		.amdhsa_uses_dynamic_stack 0
		.amdhsa_enable_private_segment 0
		.amdhsa_system_sgpr_workgroup_id_x 1
		.amdhsa_system_sgpr_workgroup_id_y 0
		.amdhsa_system_sgpr_workgroup_id_z 0
		.amdhsa_system_sgpr_workgroup_info 0
		.amdhsa_system_vgpr_workitem_id 2
		.amdhsa_next_free_vgpr 256
		.amdhsa_next_free_sgpr 102
		.amdhsa_accum_offset 256
		.amdhsa_reserve_vcc 1
		.amdhsa_float_round_mode_32 0
		.amdhsa_float_round_mode_16_64 0
		.amdhsa_float_denorm_mode_32 3
		.amdhsa_float_denorm_mode_16_64 3
		.amdhsa_dx10_clamp 1
		.amdhsa_ieee_mode 1
		.amdhsa_fp16_overflow 0
		.amdhsa_tg_split 0
		.amdhsa_exception_fp_ieee_invalid_op 0
		.amdhsa_exception_fp_denorm_src 0
		.amdhsa_exception_fp_ieee_div_zero 0
		.amdhsa_exception_fp_ieee_overflow 0
		.amdhsa_exception_fp_ieee_underflow 0
		.amdhsa_exception_fp_ieee_inexact 0
		.amdhsa_exception_int_div_zero 0
	.end_amdhsa_kernel

.Lfunc_end0:
	.size	_Z10hybrid_fwd4Args, .Lfunc_end0-_Z10hybrid_fwd4Args
	.set _Z10hybrid_fwd4Args.num_vgpr, 256
	.set _Z10hybrid_fwd4Args.num_agpr, 0
	.set _Z10hybrid_fwd4Args.numbered_sgpr, 102
	.set _Z10hybrid_fwd4Args.num_named_barrier, 0
	.set _Z10hybrid_fwd4Args.private_seg_size, 0
	.set _Z10hybrid_fwd4Args.uses_vcc, 1
	.set _Z10hybrid_fwd4Args.uses_flat_scratch, 0
	.set _Z10hybrid_fwd4Args.has_dyn_sized_stack, 0
	.set _Z10hybrid_fwd4Args.has_recursion, 0
	.set _Z10hybrid_fwd4Args.has_indirect_call, 0

amdhsa.kernels:
  - .agpr_count:     0
    .args:
      - .offset:         0
        .size:           144
        .value_kind:     by_value
      - .offset:         144
        .size:           4
        .value_kind:     hidden_block_count_x
      - .offset:         148
        .size:           4
        .value_kind:     hidden_block_count_y
      - .offset:         152
        .size:           4
        .value_kind:     hidden_block_count_z
      - .offset:         156
        .size:           2
        .value_kind:     hidden_group_size_x
      - .offset:         158
        .size:           2
        .value_kind:     hidden_group_size_y
      - .offset:         160
        .size:           2
        .value_kind:     hidden_group_size_z
      - .offset:         162
        .size:           2
        .value_kind:     hidden_remainder_x
      - .offset:         164
        .size:           2
        .value_kind:     hidden_remainder_y
      - .offset:         166
        .size:           2
        .value_kind:     hidden_remainder_z
      - .offset:         184
        .size:           8
        .value_kind:     hidden_global_offset_x
      - .offset:         192
        .size:           8
        .value_kind:     hidden_global_offset_y
      - .offset:         200
        .size:           8
        .value_kind:     hidden_global_offset_z
      - .offset:         208
        .size:           2
        .value_kind:     hidden_grid_dims
      - .offset:         232
        .size:           8
        .value_kind:     hidden_multigrid_sync_arg
      - .offset:         264
        .size:           4
        .value_kind:     hidden_dynamic_lds_size
    .group_segment_fixed_size: 16
    .kernarg_segment_align: 8
    .kernarg_segment_size: 400
    .language:       OpenCL C
    .language_version:
      - 2
      - 0
    .max_flat_workgroup_size: 512
    .name:           _Z10hybrid_fwd4Args
    .private_segment_fixed_size: 0
    .sgpr_count:     108
    .sgpr_spill_count: 3
    .symbol:         _Z10hybrid_fwd4Args.kd
    .uniform_work_group_size: 1
    .uses_dynamic_stack: false
    .vgpr_count:     256
    .vgpr_spill_count: 0
    .wavefront_size: 64
